# MLA loop without s_setprio around the MFMA groups
# speedup vs baseline: 1.0037x; 1.0009x over previous
; #define MFMA(a, b, c) __builtin_amdgcn_mfma_f32_32x32x16_bf16((a), (b), (c), 0, 0, 0)
; DI float xhalf_max(float x) { const auto rr = __builtin_amdgcn_permlane32_swap(__float_as_uint(x), __float_as_uint(x), false, false); return fmaxf(__uint_as_float(rr[0]), __uint_as_float(rr[1])); }
; template <int DQK, int DV, bool BAND> ...
;     ...
;     if constexpr (DQK < 128) {
;       f32x16 p0, p1;
; #pragma unroll
;       for (int r = 0; r < 16; ++r) { p0[r] = 0.f; p1[r] = 0.f; }
;       __builtin_amdgcn_s_setprio(1);
; #pragma unroll
;       for (int d0 = 0; d0 < ND0; ++d0) {
;         const bf16x8 k0f = *(const bf16x8*)&Ks[r32 * KLD + d0 * 16 + hi * 8];
;         const bf16x8 k1f = *(const bf16x8*)&Ks[(32 + r32) * KLD + d0 * 16 + hi * 8];
;         p0 = MFMA(k0f, qf[d0], p0); p1 = MFMA(k1f, qf[d0], p1);
;       }
;       __builtin_amdgcn_s_setprio(0);
;       float mx = fmaxf(p0[0], p1[0]);
; #pragma unroll
;       for (int r = 1; r < 16; ++r) mx = fmaxf(mx, fmaxf(p0[r], p1[r]));
;       mx = xhalf_max(mx);
;       if (__builtin_amdgcn_ballot_w64(mx > m_run + 8.f) != 0ull) {
;         const float m_new = fmaxf(m_run, mx); const float m_use = (m_new == -INFINITY) ? 0.f : m_new;
;         const float alpha = __builtin_amdgcn_exp2f(m_run - m_use);
;         l_run *= alpha; m_run = m_new;
;         if (hi == 0) sc[r32] = alpha;
;         __builtin_amdgcn_fence(__ATOMIC_RELEASE, "wavefront");
;         __builtin_amdgcn_wave_barrier();
; #pragma unroll
;         for (int g4 = 0; g4 < 4; ++g4) { const f32x4 a4 = *(const f32x4*)&sc[8 * g4 + 4 * hi];
; #pragma unroll
;           for (int cb = 0; cb < NCB; ++cb)
; #pragma unroll
;             for (int j = 0; j < 4; ++j) o[cb][4 * g4 + j] *= a4[j]; }
;         __builtin_amdgcn_wave_barrier();
;       }
;       const float m_ref = (m_run == -INFINITY) ? 0.f : m_run;
.LBB1_320:
	ds_read_b128 v[208:211], v132
	ds_read_b128 v[212:215], v132 offset:6656
	ds_read_b128 v[216:219], v132 offset:32
	ds_read_b128 v[220:223], v132 offset:6688
	ds_read_b128 v[224:227], v132 offset:64
	ds_read_b128 v[228:231], v132 offset:6720
	ds_read_b128 v[232:235], v132 offset:96
	ds_read_b128 v[236:239], v132 offset:6752
	ds_read_b128 v[240:243], v132 offset:128
	ds_read_b128 v[244:247], v132 offset:6784
	ds_read_b128 v[248:251], v132 offset:160
	ds_read_b128 v[134:137], v132 offset:6816
	s_waitcnt lgkmcnt(11)
	v_mfma_f32_32x32x16_bf16 v[34:49], v[208:211], v[66:69], v[150:165]
	s_waitcnt lgkmcnt(10)
	v_mfma_f32_32x32x16_bf16 v[50:65], v[212:215], v[66:69], v[150:165]
	s_waitcnt lgkmcnt(9)
	v_mfma_f32_32x32x16_bf16 v[34:49], v[216:219], v[70:73], v[34:49]
	s_waitcnt lgkmcnt(8)
	v_mfma_f32_32x32x16_bf16 v[50:65], v[220:223], v[70:73], v[50:65]
	s_waitcnt lgkmcnt(7)
	v_mfma_f32_32x32x16_bf16 v[34:49], v[224:227], v[74:77], v[34:49]
	s_waitcnt lgkmcnt(6)
	v_mfma_f32_32x32x16_bf16 v[50:65], v[228:231], v[74:77], v[50:65]
	s_waitcnt lgkmcnt(5)
	v_mfma_f32_32x32x16_bf16 v[34:49], v[232:235], v[78:81], v[34:49]
	s_waitcnt lgkmcnt(4)
	v_mfma_f32_32x32x16_bf16 v[50:65], v[236:239], v[78:81], v[50:65]
	s_waitcnt lgkmcnt(3)
	v_mfma_f32_32x32x16_bf16 v[34:49], v[240:243], v[82:85], v[34:49]
	s_waitcnt lgkmcnt(2)
	v_mfma_f32_32x32x16_bf16 v[50:65], v[244:247], v[82:85], v[50:65]
	s_waitcnt lgkmcnt(1)
	v_mfma_f32_32x32x16_bf16 v[34:49], v[248:251], v[86:89], v[34:49]
	s_waitcnt lgkmcnt(0)
	v_mfma_f32_32x32x16_bf16 v[50:65], v[134:137], v[86:89], v[50:65]
	ds_read2_b64 v[208:211], v166 offset0:128 offset1:130
	ds_read2_b64 v[212:215], v167 offset0:160 offset1:162
	ds_read2_b64 v[216:219], v166 offset0:136 offset1:138
	ds_read2_b64 v[220:223], v167 offset0:168 offset1:170
	ds_read2_b64 v[224:227], v166 offset0:132 offset1:134
	ds_read2_b64 v[228:231], v167 offset0:164 offset1:166
	ds_read2_b64 v[232:235], v166 offset0:140 offset1:142
	ds_read2_b64 v[236:239], v167 offset0:172 offset1:174
	s_nop 10
	v_max3_f32 v0, v34, v50, v35
	v_max3_f32 v134, v51, v36, v52
	v_max3_f32 v0, v0, v37, v53
	v_max3_f32 v134, v134, v38, v54
	v_max3_f32 v0, v0, v39, v55
	v_max3_f32 v134, v134, v40, v56
	v_max3_f32 v0, v0, v41, v57
	v_max3_f32 v134, v134, v42, v58
	v_max3_f32 v0, v0, v43, v59
	v_max3_f32 v134, v134, v44, v60
	v_max3_f32 v0, v0, v45, v61
	v_max3_f32 v134, v134, v46, v62
	v_max3_f32 v0, v0, v47, v63
	v_max3_f32 v134, v134, v48, v64
	v_max3_f32 v0, v0, v49, v65
	v_max_f32_e32 v0, v0, v134
	v_mov_b32_e32 v134, v0
	s_nop 1
	v_permlane32_swap_b32_e32 v0, v134
	v_max_f32_e32 v0, v0, v134
	v_sub_f32_e32 v0, v0, v150
	v_add_f32_e32 v134, 0x41000000, v133
	v_cmp_gt_f32_e32 vcc, v0, v134
	s_cbranch_vccz .LBB1_324
	v_max_f32_e32 v0, v0, v0
	v_max_f32_e32 v134, v133, v133
	v_max_f32_e32 v0, v134, v0
	v_cmp_neq_f32_e32 vcc, s7, v0
	s_nop 1
	v_cndmask_b32_e32 v134, 0, v0, vcc
	v_sub_f32_e32 v133, v133, v134
	v_exp_f32_e32 v133, v133
	v_add_f32_e32 v168, v150, v134
	s_and_saveexec_b64 s[22:23], s[36:37]
	ds_write_b32 v124, v133 offset:34816
	s_or_b64 exec, exec, s[22:23]
	s_waitcnt lgkmcnt(0)
	ds_read_b128 v[136:139], v120 offset:34816
	ds_read_b128 v[140:143], v120 offset:34848
	ds_read_b128 v[144:147], v120 offset:34880
	ds_read_b128 v[240:243], v120 offset:34912
	v_mul_f32_e32 v126, v126, v133
	v_sub_f32_e32 v34, v34, v168
	v_sub_f32_e32 v35, v35, v168
	v_sub_f32_e32 v36, v36, v168
	v_sub_f32_e32 v37, v37, v168
	v_sub_f32_e32 v38, v38, v168
	v_sub_f32_e32 v39, v39, v168
	v_sub_f32_e32 v40, v40, v168
	v_sub_f32_e32 v41, v41, v168
	v_sub_f32_e32 v42, v42, v168
	v_sub_f32_e32 v43, v43, v168
	v_sub_f32_e32 v44, v44, v168
	v_sub_f32_e32 v45, v45, v168
	v_sub_f32_e32 v46, v46, v168
	v_sub_f32_e32 v47, v47, v168
	v_sub_f32_e32 v48, v48, v168
	v_sub_f32_e32 v49, v49, v168
	v_sub_f32_e32 v50, v50, v168
	v_sub_f32_e32 v51, v51, v168
	v_sub_f32_e32 v52, v52, v168
	v_sub_f32_e32 v53, v53, v168
	v_sub_f32_e32 v54, v54, v168
	v_sub_f32_e32 v55, v55, v168
	v_sub_f32_e32 v56, v56, v168
	v_sub_f32_e32 v57, v57, v168
	v_sub_f32_e32 v58, v58, v168
	v_sub_f32_e32 v59, v59, v168
	v_sub_f32_e32 v60, v60, v168
	v_sub_f32_e32 v61, v61, v168
	v_sub_f32_e32 v62, v62, v168
	v_sub_f32_e32 v63, v63, v168
	v_sub_f32_e32 v64, v64, v168
	v_sub_f32_e32 v65, v65, v168
	v_sub_f32_e32 v150, 0, v134
	v_mov_b32_e32 v151, v150
	v_mov_b32_e32 v152, v150
	v_mov_b32_e32 v153, v150
	v_mov_b32_e32 v154, v150
	v_mov_b32_e32 v155, v150
	v_mov_b32_e32 v156, v150
	v_mov_b32_e32 v157, v150
	v_mov_b32_e32 v158, v150
	v_mov_b32_e32 v159, v150
	v_mov_b32_e32 v160, v150
	v_mov_b32_e32 v161, v150
	v_mov_b32_e32 v162, v150
	v_mov_b32_e32 v163, v150
	v_mov_b32_e32 v164, v150
	v_mov_b32_e32 v165, v150
	s_waitcnt lgkmcnt(0)
	v_pk_mul_f32 v[2:3], v[2:3], v[136:137]
	v_pk_mul_f32 v[4:5], v[4:5], v[138:139]
	v_pk_mul_f32 v[6:7], v[6:7], v[140:141]
	v_pk_mul_f32 v[8:9], v[8:9], v[142:143]
	v_pk_mul_f32 v[10:11], v[10:11], v[144:145]
	v_pk_mul_f32 v[12:13], v[12:13], v[146:147]
	v_pk_mul_f32 v[14:15], v[14:15], v[240:241]
	v_pk_mul_f32 v[16:17], v[16:17], v[242:243]
	v_pk_mul_f32 v[18:19], v[18:19], v[136:137]
	v_pk_mul_f32 v[20:21], v[20:21], v[138:139]
	v_pk_mul_f32 v[22:23], v[22:23], v[140:141]
	v_pk_mul_f32 v[24:25], v[24:25], v[142:143]
	v_pk_mul_f32 v[26:27], v[26:27], v[144:145]
	v_pk_mul_f32 v[28:29], v[28:29], v[146:147]
	v_pk_mul_f32 v[30:31], v[30:31], v[240:241]
	v_pk_mul_f32 v[32:33], v[32:33], v[242:243]
	s_branch .LBB1_325

; #define MFMA(a, b, c) __builtin_amdgcn_mfma_f32_32x32x16_bf16((a), (b), (c), 0, 0, 0)
; DI unsigned pk2(float a, float b) { f2_t v = {a, b}; bf2_t r = __builtin_convertvector(v, bf2_t); return __builtin_bit_cast(unsigned, r); }
; DI float xhalf_sum(float x) { const auto rr = __builtin_amdgcn_permlane32_swap(__float_as_uint(x), __float_as_uint(x), false, false); return __uint_as_float(rr[0]) + __uint_as_float(rr[1]); }
; template <int DQK, int DV, bool BAND> ...
;     ...
;       const float m_ref = (m_run == -INFINITY) ? 0.f : m_run;
;       float rs0 = 0.f, rs1 = 0.f;
; #pragma unroll
;       for (int r = 0; r < 16; ++r) { const float e0 = __builtin_amdgcn_exp2f(p0[r] - m_ref), e1 = __builtin_amdgcn_exp2f(p1[r] - m_ref); p0[r] = e0; p1[r] = e1; rs0 += e0; rs1 += e1; }
;       l_run += xhalf_sum(rs0 + rs1);
;       __builtin_amdgcn_s_setprio(1);
; #pragma unroll
;       for (int s = 0; s < 2; ++s) {
;         const u32x4 pu0 = {pk2(p0[8 * s], p0[8 * s + 1]), pk2(p0[8 * s + 2], p0[8 * s + 3]), pk2(p0[8 * s + 4], p0[8 * s + 5]), pk2(p0[8 * s + 6], p0[8 * s + 7])};
;         const u32x4 pu1 = {pk2(p1[8 * s], p1[8 * s + 1]), pk2(p1[8 * s + 2], p1[8 * s + 3]), pk2(p1[8 * s + 4], p1[8 * s + 5]), pk2(p1[8 * s + 6], p1[8 * s + 7])};
; #pragma unroll
;         for (int cb = 0; cb < NCB; ++cb) {
;           const u32x2 lo0 = *(const u32x2*)&Vs[(cb * 32 + r32) * VLD + 16 * s + 4 * hi];
;           const u32x2 hi0 = *(const u32x2*)&Vs[(cb * 32 + r32) * VLD + 16 * s + 4 * hi + 8];
;           const u32x4 v0 = {lo0[0], lo0[1], hi0[0], hi0[1]};
;           o[cb] = MFMA(__builtin_bit_cast(bf16x8, pu0), __builtin_bit_cast(bf16x8, v0), o[cb]);
;         }
; #pragma unroll
;         for (int cb = 0; cb < NCB; ++cb) {
;           const u32x2 lo1 = *(const u32x2*)&Vs[(cb * 32 + r32) * VLD + 32 + 16 * s + 4 * hi];
;           const u32x2 hi1 = *(const u32x2*)&Vs[(cb * 32 + r32) * VLD + 32 + 16 * s + 4 * hi + 8];
;           const u32x4 v1 = {lo1[0], lo1[1], hi1[0], hi1[1]};
;           o[cb] = MFMA(__builtin_bit_cast(bf16x8, pu1), __builtin_bit_cast(bf16x8, v1), o[cb]);
;         }
;       }
;       __builtin_amdgcn_s_setprio(0);
.LBB1_325:
	v_exp_f32_e32 v34, v34
	v_exp_f32_e32 v35, v35
	v_exp_f32_e32 v36, v36
	v_exp_f32_e32 v37, v37
	v_exp_f32_e32 v38, v38
	v_exp_f32_e32 v39, v39
	v_exp_f32_e32 v40, v40
	v_exp_f32_e32 v41, v41
	v_exp_f32_e32 v42, v42
	v_exp_f32_e32 v43, v43
	v_exp_f32_e32 v44, v44
	v_exp_f32_e32 v45, v45
	v_exp_f32_e32 v46, v46
	v_exp_f32_e32 v47, v47
	v_exp_f32_e32 v48, v48
	v_exp_f32_e32 v49, v49
	v_exp_f32_e32 v50, v50
	v_exp_f32_e32 v51, v51
	v_exp_f32_e32 v52, v52
	v_exp_f32_e32 v53, v53
	v_exp_f32_e32 v54, v54
	v_exp_f32_e32 v55, v55
	v_exp_f32_e32 v56, v56
	v_exp_f32_e32 v57, v57
	v_exp_f32_e32 v58, v58
	v_exp_f32_e32 v59, v59
	v_exp_f32_e32 v60, v60
	v_exp_f32_e32 v61, v61
	v_exp_f32_e32 v62, v62
	v_exp_f32_e32 v63, v63
	v_exp_f32_e32 v64, v64
	v_exp_f32_e32 v65, v65
	s_nop 0
	v_pk_add_f32 v[168:169], v[34:35], v[36:37]
	v_pk_add_f32 v[170:171], v[38:39], v[40:41]
	v_pk_add_f32 v[168:169], v[42:43], v[168:169]
	v_pk_add_f32 v[170:171], v[44:45], v[170:171]
	v_pk_add_f32 v[168:169], v[46:47], v[168:169]
	v_pk_add_f32 v[170:171], v[48:49], v[170:171]
	v_pk_add_f32 v[168:169], v[50:51], v[168:169]
	v_pk_add_f32 v[170:171], v[52:53], v[170:171]
	v_pk_add_f32 v[168:169], v[54:55], v[168:169]
	v_pk_add_f32 v[170:171], v[56:57], v[170:171]
	v_pk_add_f32 v[168:169], v[58:59], v[168:169]
	v_pk_add_f32 v[170:171], v[60:61], v[170:171]
	v_pk_add_f32 v[168:169], v[62:63], v[168:169]
	v_pk_add_f32 v[170:171], v[64:65], v[170:171]
	v_pk_add_f32 v[168:169], v[168:169], v[170:171]
	s_nop 0
	v_add_f32_e32 v168, v168, v169
	v_mov_b32_e32 v169, v168
	s_nop 1
	v_permlane32_swap_b32_e32 v168, v169
	v_add_f32_e32 v168, v168, v169
	v_add_f32_e32 v126, v126, v168
	v_cvt_pk_bf16_f32 v34, v34, v35
	v_cvt_pk_bf16_f32 v35, v36, v37
	v_cvt_pk_bf16_f32 v36, v38, v39
	v_cvt_pk_bf16_f32 v37, v40, v41
	v_cvt_pk_bf16_f32 v38, v42, v43
	v_cvt_pk_bf16_f32 v39, v44, v45
	v_cvt_pk_bf16_f32 v40, v46, v47
	v_cvt_pk_bf16_f32 v41, v48, v49
	v_cvt_pk_bf16_f32 v50, v50, v51
	v_cvt_pk_bf16_f32 v51, v52, v53
	v_cvt_pk_bf16_f32 v52, v54, v55
	v_cvt_pk_bf16_f32 v53, v56, v57
	v_cvt_pk_bf16_f32 v54, v58, v59
	v_cvt_pk_bf16_f32 v55, v60, v61
	v_cvt_pk_bf16_f32 v56, v62, v63
	v_cvt_pk_bf16_f32 v57, v64, v65
	s_waitcnt lgkmcnt(0)
	v_mfma_f32_32x32x16_bf16 v[2:17], v[34:37], v[208:211], v[2:17]
	v_mfma_f32_32x32x16_bf16 v[18:33], v[34:37], v[212:215], v[18:33]
	v_mfma_f32_32x32x16_bf16 v[2:17], v[50:53], v[216:219], v[2:17]
	v_mfma_f32_32x32x16_bf16 v[18:33], v[50:53], v[220:223], v[18:33]
	v_mfma_f32_32x32x16_bf16 v[2:17], v[38:41], v[224:227], v[2:17]
	v_mfma_f32_32x32x16_bf16 v[18:33], v[38:41], v[228:231], v[18:33]
	v_mfma_f32_32x32x16_bf16 v[2:17], v[54:57], v[232:235], v[2:17]
	v_mfma_f32_32x32x16_bf16 v[18:33], v[54:57], v[236:239], v[18:33]
	s_add_u32 s12, s12, s8
	s_addc_u32 s13, s13, s9
	s_add_u32 s14, s14, s10
	s_addc_u32 s15, s15, s11
	s_cmp_eq_u32 s75, s21
	s_cbranch_scc1 .LBB1_327
	v_mov_b32_e32 v133, v0
	s_branch .LBB1_318
